# GLA scan: static priority raise (3) for the two publisher waves (v59 + scanprio)
# speedup vs baseline: 1.0028x; 1.0028x over previous
.LBB0_459:
	s_and_b64 vcc, exec, s[66:67]
	s_cbranch_vccz .LBB0_454
	s_setprio 3
	s_lshl_b32 s18, s90, 10
	s_and_b32 s18, s18, 0x1000
	v_add_u32_e32 v0, s18, v199
	v_mad_u64_u32 v[0:1], s[54:55], v0, s89, 0
	s_add_u32 s54, s60, s95
	v_or_b32_e32 v0, v162, v0
	s_addc_u32 s55, s61, 0
	v_lshl_add_u64 v[170:171], s[54:55], 0, v[0:1]
	s_mov_b64 s[54:55], s[0:1]
	s_load_dwordx2 s[60:61], s[54:55], 0x80
	s_lshl_b32 s18, s94, 1
	v_lshl_add_u64 v[168:169], v[160:161], 0, s[64:65]
	v_lshl_add_u64 v[166:167], v[158:159], 0, s[62:63]
	s_mov_b64 s[66:67], 0xe601000
	s_waitcnt lgkmcnt(0)
	s_add_u32 s18, s60, s18
	s_addc_u32 s33, s61, 0
	s_add_u32 s54, s18, s26
	s_addc_u32 s55, s33, s27
	s_lshl_b32 s18, s93, 10
	s_and_b32 s64, s18, 0x1000
	s_lshl_b32 s18, s91, 9
	v_add_u32_e32 v2, s64, v198
	v_mov_b64_e32 v[0:1], s[60:61]
	s_and_b32 s65, s18, 0x600
	v_mad_u64_u32 v[0:1], s[62:63], v2, s89, v[0:1]
	s_lshl_b32 s18, s65, 1
	v_lshl_add_u64 v[0:1], v[0:1], 0, s[18:19]
	s_lshl_b32 s18, s91, 1
	s_and_b32 s62, s18, -16
	s_ashr_i32 s63, s62, 31
	s_lshl_b32 s18, s92, 10
	v_lshl_add_u64 v[0:1], s[62:63], 1, v[0:1]
	s_add_u32 s18, s60, s18
	s_waitcnt vmcnt(8)
	v_lshl_add_u64 v[36:37], v[0:1], 0, v[142:143]
	s_addc_u32 s33, s61, 0
	v_lshl_add_u64 v[172:173], v[36:37], 0, s[66:67]
	s_add_u32 s66, s18, s28
	s_mov_b32 s18, 0xe601000
	v_add_co_u32_e32 v0, vcc, s18, v36
	s_waitcnt vmcnt(7)
	v_lshl_add_u64 v[44:45], s[54:55], 0, v[140:141]
	v_addc_co_u32_e32 v1, vcc, 0, v37, vcc
	global_load_dwordx4 v[84:87], v[0:1], off
	v_add_co_u32_e32 v0, vcc, s78, v44
	s_addc_u32 s67, s33, s29
	s_nop 0
	v_addc_co_u32_e32 v1, vcc, 0, v45, vcc
	v_add_co_u32_e32 v16, vcc, s79, v44
	s_waitcnt vmcnt(5)
	v_lshl_add_u64 v[32:33], s[66:67], 0, v[144:145]
	v_addc_co_u32_e32 v17, vcc, 0, v45, vcc
	v_lshl_add_u64 v[178:179], v[32:33], 0, s[36:37]
	v_add_co_u32_e32 v32, vcc, s80, v32
	s_mov_b32 s18, 0xe6c1000
	s_nop 0
	v_addc_co_u32_e32 v33, vcc, 0, v33, vcc
	v_add_co_u32_e32 v36, vcc, s18, v36
	s_mov_b32 s18, 0x16708000
	s_nop 0
	v_addc_co_u32_e32 v37, vcc, 0, v37, vcc
	v_add_co_u32_e32 v38, vcc, s81, v44
	v_lshl_add_u64 v[174:175], v[44:45], 0, s[30:31]
	s_nop 0
	v_addc_co_u32_e32 v39, vcc, 0, v45, vcc
	global_load_dwordx4 v[12:15], v[0:1], off
	global_load_dwordx4 v[8:11], v[174:175], off offset:1024
	global_load_dwordx4 v[4:7], v[174:175], off offset:2048
	s_nop 0
	global_load_dwordx4 v[0:3], v[174:175], off offset:3072
	v_lshl_add_u64 v[176:177], v[44:45], 0, s[34:35]
	global_load_dwordx4 v[24:27], v[16:17], off
	global_load_dwordx4 v[28:31], v[176:177], off offset:1024
	global_load_dwordx4 v[20:23], v[176:177], off offset:2048
	s_nop 0
	global_load_dwordx4 v[16:19], v[176:177], off offset:3072
	global_load_dwordx4 v[40:43], v[32:33], off
	s_nop 0
	global_load_dwordx4 v[32:35], v[178:179], off offset:64
	global_load_dwordx4 v[80:83], v[36:37], off
	v_lshl_add_u64 v[36:37], v[44:45], 0, s[38:39]
	v_lshl_add_u64 v[52:53], v[44:45], 0, s[40:41]
	v_add_co_u32_e32 v44, vcc, s18, v44
	global_load_dwordx4 v[64:67], v[38:39], off
	global_load_dwordx4 v[68:71], v[36:37], off offset:1024
	global_load_dwordx4 v[56:59], v[36:37], off offset:2048
	s_nop 0
	global_load_dwordx4 v[36:39], v[36:37], off offset:3072
	v_addc_co_u32_e32 v45, vcc, 0, v45, vcc
	global_load_dwordx4 v[44:47], v[44:45], off
	s_nop 0
	global_load_dwordx4 v[60:63], v[52:53], off offset:1024
	global_load_dwordx4 v[48:51], v[52:53], off offset:2048
	s_nop 0
	global_load_dwordx4 v[52:55], v[52:53], off offset:3072
	s_nop 0
	global_load_dwordx4 v[76:79], v[178:179], off offset:1024
	global_load_dwordx4 v[72:75], v[178:179], off offset:1088
	v_mov_b32_e32 v128, 0
	v_add_u32_e32 v88, s70, v140
	s_mov_b32 s18, -3
	s_movk_i32 s66, 0x800
	v_mov_b32_e32 v129, v128
	v_mov_b32_e32 v130, v128
	v_mov_b32_e32 v131, v128
	v_mov_b32_e32 v132, v128
	v_mov_b32_e32 v133, v128
	v_mov_b32_e32 v134, v128
	v_mov_b32_e32 v135, v128
	s_waitcnt vmcnt(21)
	ds_write_b128 v88, v[84:87]
	s_waitcnt lgkmcnt(0)
	s_barrier
.LBB0_461:
	v_lshl_add_u64 v[188:189], s[60:61], 0, v[170:171]
	s_mov_b32 s33, 0xe781000
	v_add_co_u32_e32 v84, vcc, s33, v188
	v_lshl_add_u64 v[200:201], s[60:61], 0, v[166:167]
	s_nop 0
	v_addc_co_u32_e32 v85, vcc, 0, v189, vcc
	v_add_co_u32_e32 v86, vcc, s82, v200
	v_lshl_add_u64 v[202:203], s[60:61], 0, v[168:169]
	s_nop 0
	v_addc_co_u32_e32 v87, vcc, 0, v201, vcc
	global_load_dwordx4 v[136:139], v[84:85], off
	global_load_dwordx4 v[124:127], v[86:87], off
	global_load_dwordx4 v[112:115], v[86:87], off offset:1024
	global_load_dwordx4 v[108:111], v[86:87], off offset:2048
	v_add_co_u32_e32 v84, vcc, s83, v200
	s_add_i32 s33, s18, 3
	s_nop 0
	v_addc_co_u32_e32 v85, vcc, 0, v201, vcc
	global_load_dwordx4 v[104:107], v[86:87], off offset:3072
	global_load_dwordx4 v[100:103], v[84:85], off
	global_load_dwordx4 v[92:95], v[84:85], off offset:1024
	global_load_dwordx4 v[96:99], v[84:85], off offset:2048
	global_load_dwordx4 v[88:91], v[84:85], off offset:3072
	global_load_dwordx4 v[120:123], v[202:203], off offset:-1024
	global_load_dwordx4 v[116:119], v[202:203], off offset:-960
	s_and_b32 s54, s33, 1
	s_lshl_b32 s55, s54, 15
	s_lshl_b32 s54, s54, 11
	s_add_i32 s54, s69, s54
	v_add_u32_e32 v204, s54, v163
	ds_read_b64_tr_b16 v[84:85], v204
	v_add_u32_e32 v205, 0x80, v204
	ds_read_b64_tr_b16 v[86:87], v205
	v_add_u32_e32 v206, 0x400, v204
	ds_read_b64_tr_b16 v[184:185], v206
	v_add_u32_e32 v207, 0x480, v204
	ds_read_b64_tr_b16 v[186:187], v207
	s_waitcnt lgkmcnt(0)
	s_add_i32 s54, s55, 0
	v_cvt_pk_bf16_f32 v180, v128, v129
	v_cvt_pk_bf16_f32 v181, v130, v131
	v_cvt_pk_bf16_f32 v182, v132, v133
	v_cvt_pk_bf16_f32 v183, v134, v135
	v_lshlrev_b32_e32 v208, 2, v149
	s_waitcnt vmcnt(31)
	v_mfma_f32_16x16x32_bf16 v[12:15], v[12:15], v[180:183], 0
	s_add_i32 s55, s68, s54
	s_waitcnt vmcnt(22)
	v_pk_mul_f32 v[34:35], v[134:135], v[34:35]
	v_pk_mul_f32 v[32:33], v[132:133], v[32:33]
	v_mfma_f32_16x16x32_bf16 v[8:11], v[8:11], v[180:183], 0
	v_lshlrev_b32_e32 v209, 2, v190
	v_pk_mul_f32 v[42:43], v[130:131], v[42:43]
	v_pk_mul_f32 v[40:41], v[128:129], v[40:41]
	v_mfma_f32_16x16x32_bf16 v[4:7], v[4:7], v[180:183], 0
	s_add_i32 s18, s18, 4
	s_and_b32 s18, s18, 1
	v_mfma_f32_16x16x32_bf16 v[0:3], v[0:3], v[180:183], 0
	v_add_u32_e32 v182, s55, v208
	s_add_i32 s55, s66, 0xfffff800
	s_andn2_b32 s55, 0x800, s55
	s_add_i32 s55, s71, s55
	ds_write2st64_b32 v182, v12, v13 offset1:1
	ds_write2st64_b32 v182, v14, v15 offset0:2 offset1:3
	ds_write2st64_b32 v182, v8, v9 offset0:4 offset1:5
	ds_write2st64_b32 v182, v10, v11 offset0:6 offset1:7
	ds_write2st64_b32 v182, v4, v5 offset0:8 offset1:9
	ds_write2st64_b32 v182, v6, v7 offset0:10 offset1:11
	ds_write2st64_b32 v182, v0, v1 offset0:12 offset1:13
	ds_write2st64_b32 v182, v2, v3 offset0:14 offset1:15
	v_mfma_f32_16x16x32_bf16 v[0:3], v[20:23], v[84:87], v[32:35]
	v_add_u32_e32 v4, s55, v140
	v_add_u32_e32 v4, 0xffffe800, v4
	v_add_u32_e32 v183, s54, v209
	s_waitcnt vmcnt(21)
	ds_write_b128 v4, v[80:83]
	s_waitcnt lgkmcnt(0)
	s_barrier
	ds_read2st64_b64 v[4:7], v183 offset1:8
	v_mfma_f32_16x16x32_bf16 v[80:83], v[16:19], v[184:187], v[0:3]
	v_lshl_add_u64 v[180:181], s[60:61], 0, v[164:165]
	s_mov_b32 s54, 0xe841000
	s_waitcnt lgkmcnt(0)
	v_add_f32_e32 v4, 0, v4
	ds_read2st64_b64 v[0:3], v183 offset0:16 offset1:24
	v_add_f32_e32 v5, 0, v5
	v_add_f32_e32 v4, v4, v6
	v_add_f32_e32 v8, v5, v7
	v_mfma_f32_16x16x32_bf16 v[12:15], v[24:27], v[84:87], v[40:43]
	s_waitcnt lgkmcnt(0)
	v_add_f32_e32 v0, v4, v0
	ds_read2st64_b64 v[4:7], v183 offset0:32 offset1:40
	v_add_f32_e32 v1, v8, v1
	v_add_f32_e32 v8, v0, v2
	v_add_f32_e32 v9, v1, v3
	ds_read2st64_b64 v[0:3], v183 offset0:48 offset1:56
	s_waitcnt lgkmcnt(1)
	v_add_f32_e32 v4, v8, v4
	v_add_f32_e32 v5, v9, v5
	v_add_f32_e32 v4, v4, v6
	v_add_f32_e32 v5, v5, v7
	s_waitcnt lgkmcnt(0)
	v_add_f32_e32 v0, v4, v0
	v_add_f32_e32 v1, v5, v1
	v_add_f32_e32 v0, v0, v2
	v_add_f32_e32 v1, v1, v3
	v_cvt_pk_bf16_f32 v2, v0, v1
	v_add_co_u32_e32 v0, vcc, s84, v180
	v_mfma_f32_16x16x32_bf16 v[128:131], v[28:31], v[184:187], v[12:15]
	s_nop 0
	v_addc_co_u32_e32 v1, vcc, 0, v181, vcc
	global_store_dword v[0:1], v2, off
	v_add_co_u32_e32 v0, vcc, s54, v188
	s_lshl_b32 s54, s18, 15
	s_nop 0
	v_addc_co_u32_e32 v1, vcc, 0, v189, vcc
	v_add_co_u32_e32 v2, vcc, s85, v200
	s_lshl_b32 s18, s18, 11
	s_nop 0
	v_addc_co_u32_e32 v3, vcc, 0, v201, vcc
	v_add_co_u32_e32 v16, vcc, s86, v200
	global_load_dwordx4 v[84:87], v[0:1], off
	global_load_dwordx4 v[12:15], v[2:3], off
	global_load_dwordx4 v[8:11], v[2:3], off offset:1024
	global_load_dwordx4 v[4:7], v[2:3], off offset:2048
	v_addc_co_u32_e32 v17, vcc, 0, v201, vcc
	global_load_dwordx4 v[0:3], v[2:3], off offset:3072
	s_nop 0
	global_load_dwordx4 v[24:27], v[16:17], off
	global_load_dwordx4 v[28:31], v[16:17], off offset:1024
	global_load_dwordx4 v[20:23], v[16:17], off offset:2048
	s_nop 0
	global_load_dwordx4 v[16:19], v[16:17], off offset:3072
	s_nop 0
	global_load_dwordx4 v[40:43], v[202:203], off
	global_load_dwordx4 v[32:35], v[202:203], off offset:64
	s_add_i32 s18, s69, s18
	v_add_u32_e32 v186, s18, v163
	ds_read_b64_tr_b16 v[132:133], v186
	v_add_u32_e32 v134, 0x80, v186
	ds_read_b64_tr_b16 v[134:135], v134
	v_add_u32_e32 v184, 0x400, v186
	ds_read_b64_tr_b16 v[184:185], v184
	v_add_u32_e32 v186, 0x480, v186
	ds_read_b64_tr_b16 v[186:187], v186
	s_waitcnt lgkmcnt(0)
	s_waitcnt vmcnt(24)
	v_pk_mul_f32 v[78:79], v[78:79], v[130:131]
	v_pk_mul_f32 v[76:77], v[76:77], v[128:129]
	v_cvt_pk_bf16_f32 v200, v128, v129
	v_cvt_pk_bf16_f32 v201, v130, v131
	v_cvt_pk_bf16_f32 v202, v80, v81
	v_cvt_pk_bf16_f32 v203, v82, v83
	s_add_i32 s18, s54, 0
	v_mfma_f32_16x16x32_bf16 v[64:67], v[64:67], v[200:203], 0
	s_add_i32 s54, s68, s18
	s_waitcnt vmcnt(23)
	v_pk_mul_f32 v[72:73], v[72:73], v[80:81]
	v_add_u32_e32 v80, s54, v208
	v_mfma_f32_16x16x32_bf16 v[68:71], v[68:71], v[200:203], 0
	s_andn2_b32 s54, 0x800, s66
	v_pk_mul_f32 v[74:75], v[74:75], v[82:83]
	s_add_i32 s54, s71, s54
	v_mfma_f32_16x16x32_bf16 v[36:39], v[36:39], v[200:203], 0
	ds_write2st64_b32 v80, v64, v65 offset1:1
	ds_write2st64_b32 v80, v66, v67 offset0:2 offset1:3
	s_nop 1
	ds_write2st64_b32 v80, v68, v69 offset0:4 offset1:5
	v_mfma_f32_16x16x32_bf16 v[44:47], v[44:47], v[132:135], v[76:79]
	v_mfma_f32_16x16x32_bf16 v[56:59], v[56:59], v[200:203], 0
	ds_write2st64_b32 v80, v70, v71 offset0:6 offset1:7
	s_nop 6
	ds_write2st64_b32 v80, v56, v57 offset0:8 offset1:9
	ds_write2st64_b32 v80, v58, v59 offset0:10 offset1:11
	v_mfma_f32_16x16x32_bf16 v[200:203], v[60:63], v[184:187], v[44:47]
	ds_write2st64_b32 v80, v36, v37 offset0:12 offset1:13
	ds_write2st64_b32 v80, v38, v39 offset0:14 offset1:15
	s_nop 0
	v_add_u32_e32 v44, s54, v140
	v_mfma_f32_16x16x32_bf16 v[36:39], v[48:51], v[132:135], v[72:75]
	v_add_u32_e32 v44, 0xffffe800, v44
	v_add_u32_e32 v48, s18, v209
	s_waitcnt vmcnt(22)
	ds_write_b128 v44, v[136:139]
	s_waitcnt lgkmcnt(0)
	s_barrier
	ds_read2st64_b64 v[44:47], v48 offset1:8
	v_mfma_f32_16x16x32_bf16 v[136:139], v[52:55], v[184:187], v[36:39]
	s_min_u32 s18, s33, 59
	s_add_i32 s54, s18, 4
	s_mul_i32 s18, s54, 0xc0000
	ds_read2st64_b64 v[36:39], v48 offset0:16 offset1:24
	s_waitcnt lgkmcnt(1)
	v_add_f32_e32 v44, 0, v44
	v_add_f32_e32 v45, 0, v45
	v_add_f32_e32 v44, v44, v46
	v_add_f32_e32 v49, v45, v47
	s_waitcnt lgkmcnt(0)
	v_add_f32_e32 v36, v44, v36
	ds_read2st64_b64 v[44:47], v48 offset0:32 offset1:40
	v_add_f32_e32 v37, v49, v37
	v_add_f32_e32 v49, v36, v38
	v_add_f32_e32 v50, v37, v39
	ds_read2st64_b64 v[36:39], v48 offset0:48 offset1:56
	s_waitcnt lgkmcnt(1)
	v_add_f32_e32 v44, v49, v44
	v_add_f32_e32 v45, v50, v45
	v_add_f32_e32 v44, v44, v46
	v_add_f32_e32 v45, v45, v47
	s_waitcnt lgkmcnt(0)
	v_add_f32_e32 v36, v44, v36
	v_add_f32_e32 v37, v45, v37
	v_add_f32_e32 v36, v36, v38
	v_add_f32_e32 v37, v37, v39
	v_cvt_pk_bf16_f32 v38, v36, v37
	v_add_co_u32_e32 v36, vcc, s87, v180
	s_nop 1
	v_addc_co_u32_e32 v37, vcc, 0, v181, vcc
	global_store_dword v[36:37], v38, off
	v_lshl_add_u64 v[36:37], v[172:173], 0, s[18:19]
	s_lshl_b32 s18, s54, 15
	v_lshl_add_u64 v[38:39], v[174:175], 0, s[18:19]
	v_lshl_add_u64 v[52:53], v[176:177], 0, s[18:19]
	s_lshl_b32 s18, s54, 10
	global_load_dwordx4 v[80:83], v[36:37], off
	global_load_dwordx4 v[64:67], v[38:39], off
	global_load_dwordx4 v[68:71], v[38:39], off offset:1024
	global_load_dwordx4 v[56:59], v[38:39], off offset:2048
	s_nop 0
	global_load_dwordx4 v[36:39], v[38:39], off offset:3072
	s_nop 0
	global_load_dwordx4 v[44:47], v[52:53], off
	global_load_dwordx4 v[60:63], v[52:53], off offset:1024
	global_load_dwordx4 v[48:51], v[52:53], off offset:2048
	v_lshl_add_u64 v[72:73], v[178:179], 0, s[18:19]
	global_load_dwordx4 v[52:55], v[52:53], off offset:3072
	s_nop 0
	global_load_dwordx4 v[76:79], v[72:73], off
	s_nop 0
	global_load_dwordx4 v[72:75], v[72:73], off offset:64
	ds_read_b64_tr_b16 v[128:129], v204
	ds_read_b64_tr_b16 v[130:131], v205
	ds_read_b64_tr_b16 v[132:133], v206
	ds_read_b64_tr_b16 v[134:135], v207
	s_waitcnt lgkmcnt(0)
	s_waitcnt vmcnt(25)
	v_pk_mul_f32 v[122:123], v[122:123], v[202:203]
	v_pk_mul_f32 v[120:121], v[120:121], v[200:201]
	v_cvt_pk_bf16_f32 v184, v200, v201
	v_cvt_pk_bf16_f32 v185, v202, v203
	v_cvt_pk_bf16_f32 v186, v136, v137
	v_cvt_pk_bf16_f32 v187, v138, v139
	s_add_i32 s54, s66, 0x800
	v_mfma_f32_16x16x32_bf16 v[124:127], v[124:127], v[184:187], 0
	s_andn2_b32 s54, 0x800, s54
	s_waitcnt vmcnt(24)
	v_pk_mul_f32 v[118:119], v[118:119], v[138:139]
	v_pk_mul_f32 v[116:117], v[116:117], v[136:137]
	v_mfma_f32_16x16x32_bf16 v[100:103], v[100:103], v[128:131], v[120:123]
	s_add_i32 s54, s71, s54
	v_add_co_u32_e32 v136, vcc, s88, v180
	v_mfma_f32_16x16x32_bf16 v[112:115], v[112:115], v[184:187], 0
	s_addk_i32 s66, 0x1800
	v_addc_co_u32_e32 v137, vcc, 0, v181, vcc
	v_mfma_f32_16x16x32_bf16 v[96:99], v[96:99], v[128:131], v[116:119]
	v_lshl_add_u64 v[164:165], v[164:165], 0, s[42:43]
	v_lshl_add_u64 v[166:167], v[166:167], 0, s[48:49]
	v_lshl_add_u64 v[168:169], v[168:169], 0, s[50:51]
	v_add_u32_e32 v116, s54, v140
	v_mfma_f32_16x16x32_bf16 v[108:111], v[108:111], v[184:187], 0
	v_add_u32_e32 v116, 0xffffe800, v116
	v_lshl_add_u64 v[170:171], v[170:171], 0, s[58:59]
	s_mov_b32 s18, s33
	v_mfma_f32_16x16x32_bf16 v[104:107], v[104:107], v[184:187], 0
	ds_write2st64_b32 v182, v124, v125 offset1:1
	ds_write2st64_b32 v182, v126, v127 offset0:2 offset1:3
	ds_write2st64_b32 v182, v112, v113 offset0:4 offset1:5
	ds_write2st64_b32 v182, v114, v115 offset0:6 offset1:7
	ds_write2st64_b32 v182, v108, v109 offset0:8 offset1:9
	ds_write2st64_b32 v182, v110, v111 offset0:10 offset1:11
	s_nop 1
	ds_write2st64_b32 v182, v104, v105 offset0:12 offset1:13
	ds_write2st64_b32 v182, v106, v107 offset0:14 offset1:15
	s_waitcnt vmcnt(22)
	ds_write_b128 v116, v[84:87]
	s_waitcnt lgkmcnt(0)
	s_barrier
	v_mfma_f32_16x16x32_bf16 v[128:131], v[92:95], v[132:135], v[100:103]
	ds_read2st64_b64 v[92:95], v183 offset1:8
	s_cmp_lt_u32 s33, 60
	v_mfma_f32_16x16x32_bf16 v[132:135], v[88:91], v[132:135], v[96:99]
	ds_read2st64_b64 v[88:91], v183 offset0:16 offset1:24
	s_nop 1
	ds_read2st64_b64 v[96:99], v183 offset0:32 offset1:40
	ds_read2st64_b64 v[100:103], v183 offset0:48 offset1:56
	s_waitcnt lgkmcnt(3)
	v_add_f32_e32 v92, 0, v92
	v_add_f32_e32 v93, 0, v93
	v_add_f32_e32 v92, v92, v94
	v_add_f32_e32 v93, v93, v95
	s_waitcnt lgkmcnt(2)
	v_add_f32_e32 v88, v92, v88
	v_add_f32_e32 v89, v93, v89
	v_add_f32_e32 v88, v88, v90
	v_add_f32_e32 v89, v89, v91
	s_waitcnt lgkmcnt(1)
	v_add_f32_e32 v88, v88, v96
	v_add_f32_e32 v89, v89, v97
	v_add_f32_e32 v88, v88, v98
	v_add_f32_e32 v89, v89, v99
	s_waitcnt lgkmcnt(0)
	v_add_f32_e32 v88, v88, v100
	v_add_f32_e32 v89, v89, v101
	v_add_f32_e32 v88, v88, v102
	v_add_f32_e32 v89, v89, v103
	v_cvt_pk_bf16_f32 v88, v88, v89
	global_store_dword v[136:137], v88, off
	s_cbranch_scc1 .LBB0_461
	s_waitcnt vmcnt(15)
	ds_read_b64_tr_b16 v[16:17], v191
	s_lshl_b32 s18, s64, 12
	ds_read_b64_tr_b16 v[16:17], v193
	s_add_u32 s18, s60, s18
	ds_read_b64_tr_b16 v[16:17], v194
	s_addc_u32 s33, s61, 0
	s_lshl_b32 s54, s65, 1
	ds_read_b64_tr_b16 v[16:17], v195
	s_add_u32 s18, s18, s54
	s_waitcnt lgkmcnt(0)
	s_addc_u32 s33, s33, 0
	s_lshl_b64 s[54:55], s[62:63], 1
	s_add_u32 s54, s18, s54
	s_addc_u32 s55, s33, s55
	v_cvt_pk_bf16_f32 v16, v128, v129
	v_cvt_pk_bf16_f32 v17, v130, v131
	v_cvt_pk_bf16_f32 v18, v132, v133
	v_cvt_pk_bf16_f32 v19, v134, v135
	v_add_u32_e32 v20, s68, v196
	v_mfma_f32_16x16x32_bf16 v[12:15], v[12:15], v[16:19], 0
	v_mfma_f32_16x16x32_bf16 v[8:11], v[8:11], v[16:19], 0
	s_nop 6
	ds_write2st64_b32 v20, v12, v13 offset0:128 offset1:129
	ds_write2st64_b32 v20, v14, v15 offset0:130 offset1:131
	ds_write2st64_b32 v20, v8, v9 offset0:132 offset1:133
	v_mfma_f32_16x16x32_bf16 v[0:3], v[0:3], v[16:19], 0
	v_mfma_f32_16x16x32_bf16 v[4:7], v[4:7], v[16:19], 0
	ds_write2st64_b32 v20, v10, v11 offset0:134 offset1:135
	s_nop 6
	ds_write2st64_b32 v20, v4, v5 offset0:136 offset1:137
	ds_write2st64_b32 v20, v6, v7 offset0:138 offset1:139
	ds_write2st64_b32 v20, v0, v1 offset0:140 offset1:141
	ds_write2st64_b32 v20, v2, v3 offset0:142 offset1:143
	v_add_u32_e32 v0, s72, v140
	ds_write_b128 v0, v[84:87]
	s_waitcnt lgkmcnt(0)
	s_barrier
	ds_read2st64_b64 v[0:3], v197 offset0:64 offset1:72
	ds_read2st64_b64 v[4:7], v197 offset0:80 offset1:88
	s_waitcnt lgkmcnt(1)
	v_add_f32_e32 v0, 0, v0
	v_add_f32_e32 v1, 0, v1
	v_add_f32_e32 v0, v0, v2
	v_add_f32_e32 v8, v1, v3
	s_waitcnt lgkmcnt(0)
	v_add_f32_e32 v4, v0, v4
	ds_read2st64_b64 v[0:3], v197 offset0:96 offset1:104
	v_add_f32_e32 v5, v8, v5
	v_add_f32_e32 v8, v4, v6
	v_add_f32_e32 v9, v5, v7
	ds_read2st64_b64 v[4:7], v197 offset0:112 offset1:120
	s_waitcnt lgkmcnt(1)
	v_add_f32_e32 v0, v8, v0
	v_add_f32_e32 v1, v9, v1
	v_add_f32_e32 v0, v0, v2
	v_add_f32_e32 v1, v1, v3
	s_waitcnt lgkmcnt(0)
	v_add_f32_e32 v0, v0, v4
	v_add_f32_e32 v1, v1, v5
	v_add_f32_e32 v0, v0, v6
	v_add_f32_e32 v1, v1, v7
	v_cvt_pk_bf16_f32 v4, v0, v1
	v_lshl_add_u64 v[0:1], s[54:55], 0, v[146:147]
	v_lshlrev_b32_e32 v2, 1, v148
	v_mov_b32_e32 v3, v143
	v_lshl_add_u64 v[0:1], v[0:1], 0, v[2:3]
	v_add_co_u32_e32 v0, vcc, 0x1a7c0000, v0
	s_nop 1
	v_addc_co_u32_e32 v1, vcc, 0, v1, vcc
	global_store_dword v[0:1], v4, off
	s_barrier
	s_setprio 0
	s_branch .LBB0_454
